# up epilogue: lane-transposed stores software-pipelined one block behind (permuted data in spare VGPRs, flush flag), no exposed LDS wait
# baseline (speedup 1.0000x reference)
; __device__ __forceinline__ float ss_rinv(u64 v) { return __builtin_amdgcn_rsqf((float)v * SS_INV + 1e-6f); }
; __device__ __forceinline__ unsigned cvtpk(float lo, float hi) { f32x2 v = {lo, hi}; bf16x2_t b = __builtin_convertvector(v, bf16x2_t); return __builtin_bit_cast(unsigned, b); }
;     __device__ __forceinline__ void operator()(const f32x4 (&acc)[2][2][4][2], const pg8::Unit& u, int wr, int wc, int fr, int fq) const {
;     ...
;                 const int lrow = u.pm * 256 + ai * 128 + wr * 64 + m * 16 + fr, grow = row_base + lrow;
;                 if (grow >= MREAL) continue;
;                 const float ri = ss_rinv(rowss[grow]);
; #pragma unroll
;                 for (int bj = 0; bj < 2; ++bj) {
;                     const int col0 = u.pn * 256 + bj * 128 + wc * 32 + 8 * fq;
;                     f32x4 v0 = acc[ai][bj][m][0] * ri, v1 = acc[ai][bj][m][1] * ri;
;                     if (MODE == 1) {
; #pragma unroll
;                         for (int i = 0; i < 4; ++i) { const float a = fmaxf(v0[i], 0.f), b = fmaxf(v1[i], 0.f); v0[i] = a * a; v1[i] = b * b; }
;                         u32x4 w; w.x = cvtpk(v0[0], v0[1]); w.y = cvtpk(v0[2], v0[3]); w.z = cvtpk(v1[0], v1[1]); w.w = cvtpk(v1[2], v1[3]);
;                         *(u32x4*)(O + (size_t)lrow * DFF + col0) = w;
.LBB0_2035:
	s_mov_b32 s95, 0
	v_mbcnt_lo_u32_b32 v215, -1, 0
	v_mbcnt_hi_u32_b32 v215, -1, v215
	v_and_b32_e32 v214, 3, v215
	v_lshlrev_b32_e32 v214, 6, v214
	v_and_b32_e32 v155, 60, v215
	v_or_b32_e32 v214, v214, v155
	v_lshrrev_b32_e32 v155, 2, v215
	v_and_b32_e32 v156, 15, v215
	v_sub_u32_e32 v155, v155, v156
	v_lshlrev_b32_e32 v250, 13, v155
	v_and_b32_e32 v155, 3, v215
	v_lshrrev_b32_e32 v156, 4, v215
	v_sub_u32_e32 v155, v155, v156
	v_lshl_add_u32 v250, v155, 4, v250
	v_ashrrev_i32_e32 v251, 31, v250
	v_lshl_add_u32 v142, s38, 8, v158
	v_lshl_or_b32 v140, s36, 8, v160
	v_add_u32_e32 v144, s66, v142
	v_cmp_gt_i32_e32 vcc, s54, v144
	v_ashrrev_i32_e32 v145, 31, v144
	v_ashrrev_i32_e32 v141, 31, v140
	v_lshl_add_u64 v[186:187], v[144:145], 3, s[12:13]
	global_load_dwordx2 v[170:171], v[186:187], off
	global_load_dwordx2 v[172:173], v[186:187], off offset:128
	global_load_dwordx2 v[174:175], v[186:187], off offset:256
	global_load_dwordx2 v[176:177], v[186:187], off offset:384
	global_load_dwordx2 v[178:179], v[186:187], off offset:1024
	global_load_dwordx2 v[180:181], v[186:187], off offset:1152
	global_load_dwordx2 v[182:183], v[186:187], off offset:1280
	global_load_dwordx2 v[184:185], v[186:187], off offset:1408
	s_waitcnt vmcnt(0)
	s_and_saveexec_b64 s[36:37], vcc
	s_cbranch_execz .LBB0_2037
	v_mov_b64_e32 v[146:147], v[170:171]
	v_ffbh_u32_e32 v143, v147
	v_min_u32_e32 v148, 32, v143
	v_lshlrev_b64 v[146:147], v148, v[146:147]
	v_min_u32_e32 v143, 1, v146
	v_or_b32_e32 v143, v147, v143
	v_cvt_f32_u32_e32 v146, v143
	v_sub_u32_e32 v147, 32, v148
	v_ashrrev_i32_e32 v143, 31, v142
	v_lshlrev_b64 v[148:149], 13, v[142:143]
	v_ldexp_f32 v146, v146, v147
	v_fmamk_f32 v146, v146, 0x30800000, v203
	v_rsq_f32_e32 v146, v146
	v_lshl_add_u64 v[148:149], s[8:9], 0, v[148:149]
	v_lshl_add_u64 v[148:149], v[140:141], 1, v[148:149]
	v_pk_mul_f32 v[128:129], v[128:129], v[146:147] op_sel_hi:[1,0]
	v_pk_mul_f32 v[126:127], v[126:127], v[146:147] op_sel_hi:[1,0]
	v_pk_mul_f32 v[124:125], v[124:125], v[146:147] op_sel_hi:[1,0]
	v_pk_mul_f32 v[122:123], v[122:123], v[146:147] op_sel_hi:[1,0]
	v_pk_mul_f32 v[120:121], v[120:121], v[146:147] op_sel_hi:[1,0]
	v_pk_mul_f32 v[118:119], v[118:119], v[146:147] op_sel_hi:[1,0]
	v_pk_mul_f32 v[116:117], v[116:117], v[146:147] op_sel_hi:[1,0]
	v_pk_mul_f32 v[114:115], v[114:115], v[146:147] op_sel_hi:[1,0]
	v_max_f32_e32 v126, 0, v126
	v_max_f32_e32 v122, 0, v122
	v_max_f32_e32 v127, 0, v127
	v_max_f32_e32 v123, 0, v123
	v_max_f32_e32 v128, 0, v128
	v_max_f32_e32 v124, 0, v124
	v_max_f32_e32 v129, 0, v129
	v_max_f32_e32 v125, 0, v125
	v_max_f32_e32 v118, 0, v118
	v_max_f32_e32 v114, 0, v114
	v_max_f32_e32 v119, 0, v119
	v_max_f32_e32 v115, 0, v115
	v_max_f32_e32 v120, 0, v120
	v_max_f32_e32 v116, 0, v116
	v_max_f32_e32 v121, 0, v121
	v_max_f32_e32 v117, 0, v117
	v_pk_mul_f32 v[126:127], v[126:127], v[126:127]
	v_pk_mul_f32 v[122:123], v[122:123], v[122:123]
	v_pk_mul_f32 v[128:129], v[128:129], v[128:129]
	v_pk_mul_f32 v[124:125], v[124:125], v[124:125]
	v_pk_mul_f32 v[118:119], v[118:119], v[118:119]
	v_pk_mul_f32 v[146:147], v[114:115], v[114:115]
	v_pk_mul_f32 v[120:121], v[120:121], v[120:121]
	v_pk_mul_f32 v[150:151], v[116:117], v[116:117]
	v_cvt_pk_bf16_f32 v114, v126, v127
	v_cvt_pk_bf16_f32 v115, v128, v129
	v_cvt_pk_bf16_f32 v116, v122, v123
	v_cvt_pk_bf16_f32 v117, v124, v125
	v_cvt_pk_bf16_f32 v118, v118, v119
	v_cvt_pk_bf16_f32 v119, v120, v121
	v_cvt_pk_bf16_f32 v120, v146, v147
	v_cvt_pk_bf16_f32 v121, v150, v151
	ds_bpermute_b32 v230, v214, v114
	ds_bpermute_b32 v231, v214, v115
	ds_bpermute_b32 v232, v214, v116
	ds_bpermute_b32 v233, v214, v117
	ds_bpermute_b32 v234, v214, v118
	ds_bpermute_b32 v235, v214, v119
	ds_bpermute_b32 v236, v214, v120
	ds_bpermute_b32 v237, v214, v121
	v_lshl_add_u64 v[238:239], v[250:251], 0, v[148:149]
	s_mov_b32 s95, 1
.LBB0_2037:
	s_or_b64 exec, exec, s[36:37]
	v_or_b32_e32 v114, 16, v142
	v_cmp_ge_i32_e32 vcc, s76, v114
	s_and_saveexec_b64 s[36:37], vcc
	s_cbranch_execz .LBB0_2039
	v_mov_b64_e32 v[116:117], v[172:173]
	v_ffbh_u32_e32 v115, v117
	v_min_u32_e32 v118, 32, v115
	v_lshlrev_b64 v[116:117], v118, v[116:117]
	v_min_u32_e32 v115, 1, v116
	v_or_b32_e32 v115, v117, v115
	v_cvt_f32_u32_e32 v116, v115
	v_sub_u32_e32 v117, 32, v118
	v_ashrrev_i32_e32 v115, 31, v114
	v_lshlrev_b64 v[114:115], 13, v[114:115]
	v_ldexp_f32 v116, v116, v117
	v_fmamk_f32 v116, v116, 0x30800000, v203
	v_rsq_f32_e32 v116, v116
	v_lshl_add_u64 v[114:115], s[8:9], 0, v[114:115]
	v_lshl_add_u64 v[114:115], v[140:141], 1, v[114:115]
	v_pk_mul_f32 v[112:113], v[112:113], v[116:117] op_sel_hi:[1,0]
	v_pk_mul_f32 v[110:111], v[110:111], v[116:117] op_sel_hi:[1,0]
	v_pk_mul_f32 v[108:109], v[108:109], v[116:117] op_sel_hi:[1,0]
	v_pk_mul_f32 v[106:107], v[106:107], v[116:117] op_sel_hi:[1,0]
	v_pk_mul_f32 v[104:105], v[104:105], v[116:117] op_sel_hi:[1,0]
	v_pk_mul_f32 v[102:103], v[102:103], v[116:117] op_sel_hi:[1,0]
	v_pk_mul_f32 v[100:101], v[100:101], v[116:117] op_sel_hi:[1,0]
	v_pk_mul_f32 v[98:99], v[98:99], v[116:117] op_sel_hi:[1,0]
	v_max_f32_e32 v110, 0, v110
	v_max_f32_e32 v106, 0, v106
	v_max_f32_e32 v111, 0, v111
	v_max_f32_e32 v107, 0, v107
	v_max_f32_e32 v112, 0, v112
	v_max_f32_e32 v108, 0, v108
	v_max_f32_e32 v113, 0, v113
	v_max_f32_e32 v109, 0, v109
	v_max_f32_e32 v102, 0, v102
	v_max_f32_e32 v98, 0, v98
	v_max_f32_e32 v103, 0, v103
	v_max_f32_e32 v99, 0, v99
	v_max_f32_e32 v104, 0, v104
	v_max_f32_e32 v100, 0, v100
	v_max_f32_e32 v105, 0, v105
	v_max_f32_e32 v101, 0, v101
	v_pk_mul_f32 v[110:111], v[110:111], v[110:111]
	v_pk_mul_f32 v[106:107], v[106:107], v[106:107]
	v_pk_mul_f32 v[112:113], v[112:113], v[112:113]
	v_pk_mul_f32 v[108:109], v[108:109], v[108:109]
	v_pk_mul_f32 v[102:103], v[102:103], v[102:103]
	v_pk_mul_f32 v[116:117], v[98:99], v[98:99]
	v_pk_mul_f32 v[104:105], v[104:105], v[104:105]
	v_pk_mul_f32 v[118:119], v[100:101], v[100:101]
	v_cvt_pk_bf16_f32 v98, v110, v111
	v_cvt_pk_bf16_f32 v99, v112, v113
	v_cvt_pk_bf16_f32 v100, v106, v107
	v_cvt_pk_bf16_f32 v101, v108, v109
	v_cvt_pk_bf16_f32 v102, v102, v103
	v_cvt_pk_bf16_f32 v103, v104, v105
	v_cvt_pk_bf16_f32 v104, v116, v117
	v_cvt_pk_bf16_f32 v105, v118, v119
	s_waitcnt lgkmcnt(0)
	global_store_dwordx4 v[238:239], v[230:233], off
	global_store_dwordx4 v[238:239], v[234:237], off offset:256
	ds_bpermute_b32 v230, v214, v98
	ds_bpermute_b32 v231, v214, v99
	ds_bpermute_b32 v232, v214, v100
	ds_bpermute_b32 v233, v214, v101
	ds_bpermute_b32 v234, v214, v102
	ds_bpermute_b32 v235, v214, v103
	ds_bpermute_b32 v236, v214, v104
	ds_bpermute_b32 v237, v214, v105
	v_lshl_add_u64 v[238:239], v[250:251], 0, v[114:115]
; __device__ __forceinline__ float ss_rinv(u64 v) { return __builtin_amdgcn_rsqf((float)v * SS_INV + 1e-6f); }
; __device__ __forceinline__ unsigned cvtpk(float lo, float hi) { f32x2 v = {lo, hi}; bf16x2_t b = __builtin_convertvector(v, bf16x2_t); return __builtin_bit_cast(unsigned, b); }
;     __device__ __forceinline__ void operator()(const f32x4 (&acc)[2][2][4][2], const pg8::Unit& u, int wr, int wc, int fr, int fq) const {
;     ...
;                 const int lrow = u.pm * 256 + ai * 128 + wr * 64 + m * 16 + fr, grow = row_base + lrow;
;                 if (grow >= MREAL) continue;
;                 const float ri = ss_rinv(rowss[grow]);
; #pragma unroll
;                 for (int bj = 0; bj < 2; ++bj) {
;                     const int col0 = u.pn * 256 + bj * 128 + wc * 32 + 8 * fq;
;                     f32x4 v0 = acc[ai][bj][m][0] * ri, v1 = acc[ai][bj][m][1] * ri;
;                     if (MODE == 1) {
; #pragma unroll
;                         for (int i = 0; i < 4; ++i) { const float a = fmaxf(v0[i], 0.f), b = fmaxf(v1[i], 0.f); v0[i] = a * a; v1[i] = b * b; }
;                         u32x4 w; w.x = cvtpk(v0[0], v0[1]); w.y = cvtpk(v0[2], v0[3]); w.z = cvtpk(v1[0], v1[1]); w.w = cvtpk(v1[2], v1[3]);
;                         *(u32x4*)(O + (size_t)lrow * DFF + col0) = w;
.LBB0_2039:
	s_or_b64 exec, exec, s[36:37]
	v_or_b32_e32 v98, 32, v142
	v_cmp_ge_i32_e32 vcc, s76, v98
	s_and_saveexec_b64 s[36:37], vcc
	s_cbranch_execz .LBB0_2041
	v_mov_b64_e32 v[100:101], v[174:175]
	v_ffbh_u32_e32 v99, v101
	v_min_u32_e32 v102, 32, v99
	v_lshlrev_b64 v[100:101], v102, v[100:101]
	v_min_u32_e32 v99, 1, v100
	v_or_b32_e32 v99, v101, v99
	v_cvt_f32_u32_e32 v100, v99
	v_sub_u32_e32 v101, 32, v102
	v_ashrrev_i32_e32 v99, 31, v98
	v_lshlrev_b64 v[98:99], 13, v[98:99]
	v_ldexp_f32 v100, v100, v101
	v_fmamk_f32 v100, v100, 0x30800000, v203
	v_rsq_f32_e32 v100, v100
	v_lshl_add_u64 v[98:99], s[8:9], 0, v[98:99]
	v_lshl_add_u64 v[98:99], v[140:141], 1, v[98:99]
	v_pk_mul_f32 v[96:97], v[96:97], v[100:101] op_sel_hi:[1,0]
	v_pk_mul_f32 v[94:95], v[94:95], v[100:101] op_sel_hi:[1,0]
	v_pk_mul_f32 v[92:93], v[92:93], v[100:101] op_sel_hi:[1,0]
	v_pk_mul_f32 v[90:91], v[90:91], v[100:101] op_sel_hi:[1,0]
	v_pk_mul_f32 v[88:89], v[88:89], v[100:101] op_sel_hi:[1,0]
	v_pk_mul_f32 v[86:87], v[86:87], v[100:101] op_sel_hi:[1,0]
	v_pk_mul_f32 v[84:85], v[84:85], v[100:101] op_sel_hi:[1,0]
	v_pk_mul_f32 v[82:83], v[82:83], v[100:101] op_sel_hi:[1,0]
	v_max_f32_e32 v94, 0, v94
	v_max_f32_e32 v90, 0, v90
	v_max_f32_e32 v95, 0, v95
	v_max_f32_e32 v91, 0, v91
	v_max_f32_e32 v96, 0, v96
	v_max_f32_e32 v92, 0, v92
	v_max_f32_e32 v97, 0, v97
	v_max_f32_e32 v93, 0, v93
	v_max_f32_e32 v86, 0, v86
	v_max_f32_e32 v82, 0, v82
	v_max_f32_e32 v87, 0, v87
	v_max_f32_e32 v83, 0, v83
	v_max_f32_e32 v88, 0, v88
	v_max_f32_e32 v84, 0, v84
	v_max_f32_e32 v89, 0, v89
	v_max_f32_e32 v85, 0, v85
	v_pk_mul_f32 v[94:95], v[94:95], v[94:95]
	v_pk_mul_f32 v[90:91], v[90:91], v[90:91]
	v_pk_mul_f32 v[96:97], v[96:97], v[96:97]
	v_pk_mul_f32 v[92:93], v[92:93], v[92:93]
	v_pk_mul_f32 v[86:87], v[86:87], v[86:87]
	v_pk_mul_f32 v[100:101], v[82:83], v[82:83]
	v_pk_mul_f32 v[88:89], v[88:89], v[88:89]
	v_pk_mul_f32 v[102:103], v[84:85], v[84:85]
	v_cvt_pk_bf16_f32 v82, v94, v95
	v_cvt_pk_bf16_f32 v83, v96, v97
	v_cvt_pk_bf16_f32 v84, v90, v91
	v_cvt_pk_bf16_f32 v85, v92, v93
	v_cvt_pk_bf16_f32 v86, v86, v87
	v_cvt_pk_bf16_f32 v87, v88, v89
	v_cvt_pk_bf16_f32 v88, v100, v101
	v_cvt_pk_bf16_f32 v89, v102, v103
	s_waitcnt lgkmcnt(0)
	global_store_dwordx4 v[238:239], v[230:233], off
	global_store_dwordx4 v[238:239], v[234:237], off offset:256
	ds_bpermute_b32 v230, v214, v82
	ds_bpermute_b32 v231, v214, v83
	ds_bpermute_b32 v232, v214, v84
	ds_bpermute_b32 v233, v214, v85
	ds_bpermute_b32 v234, v214, v86
	ds_bpermute_b32 v235, v214, v87
	ds_bpermute_b32 v236, v214, v88
	ds_bpermute_b32 v237, v214, v89
	v_lshl_add_u64 v[238:239], v[250:251], 0, v[98:99]
.LBB0_2041:
	s_or_b64 exec, exec, s[36:37]
	v_or_b32_e32 v82, 48, v142
	v_cmp_ge_i32_e32 vcc, s76, v82
	s_and_saveexec_b64 s[36:37], vcc
	s_cbranch_execz .LBB0_2043
	v_mov_b64_e32 v[84:85], v[176:177]
	v_ffbh_u32_e32 v83, v85
	v_min_u32_e32 v86, 32, v83
	v_lshlrev_b64 v[84:85], v86, v[84:85]
	v_min_u32_e32 v83, 1, v84
	v_or_b32_e32 v83, v85, v83
	v_cvt_f32_u32_e32 v84, v83
	v_sub_u32_e32 v85, 32, v86
	v_ashrrev_i32_e32 v83, 31, v82
	v_lshlrev_b64 v[82:83], 13, v[82:83]
	v_ldexp_f32 v84, v84, v85
	v_fmamk_f32 v84, v84, 0x30800000, v203
	v_rsq_f32_e32 v84, v84
	v_lshl_add_u64 v[82:83], s[8:9], 0, v[82:83]
	v_lshl_add_u64 v[82:83], v[140:141], 1, v[82:83]
	v_pk_mul_f32 v[80:81], v[80:81], v[84:85] op_sel_hi:[1,0]
	v_pk_mul_f32 v[78:79], v[78:79], v[84:85] op_sel_hi:[1,0]
	v_pk_mul_f32 v[76:77], v[76:77], v[84:85] op_sel_hi:[1,0]
	v_pk_mul_f32 v[74:75], v[74:75], v[84:85] op_sel_hi:[1,0]
	v_pk_mul_f32 v[72:73], v[72:73], v[84:85] op_sel_hi:[1,0]
	v_pk_mul_f32 v[70:71], v[70:71], v[84:85] op_sel_hi:[1,0]
	v_pk_mul_f32 v[68:69], v[68:69], v[84:85] op_sel_hi:[1,0]
	v_pk_mul_f32 v[66:67], v[66:67], v[84:85] op_sel_hi:[1,0]
	v_max_f32_e32 v78, 0, v78
	v_max_f32_e32 v74, 0, v74
	v_max_f32_e32 v79, 0, v79
	v_max_f32_e32 v75, 0, v75
	v_max_f32_e32 v80, 0, v80
	v_max_f32_e32 v76, 0, v76
	v_max_f32_e32 v81, 0, v81
	v_max_f32_e32 v77, 0, v77
	v_max_f32_e32 v70, 0, v70
	v_max_f32_e32 v66, 0, v66
	v_max_f32_e32 v71, 0, v71
	v_max_f32_e32 v67, 0, v67
	v_max_f32_e32 v72, 0, v72
	v_max_f32_e32 v68, 0, v68
	v_max_f32_e32 v73, 0, v73
	v_max_f32_e32 v69, 0, v69
	v_pk_mul_f32 v[78:79], v[78:79], v[78:79]
	v_pk_mul_f32 v[74:75], v[74:75], v[74:75]
	v_pk_mul_f32 v[80:81], v[80:81], v[80:81]
	v_pk_mul_f32 v[76:77], v[76:77], v[76:77]
	v_pk_mul_f32 v[70:71], v[70:71], v[70:71]
	v_pk_mul_f32 v[84:85], v[66:67], v[66:67]
	v_pk_mul_f32 v[72:73], v[72:73], v[72:73]
	v_pk_mul_f32 v[86:87], v[68:69], v[68:69]
	v_cvt_pk_bf16_f32 v66, v78, v79
	v_cvt_pk_bf16_f32 v67, v80, v81
	v_cvt_pk_bf16_f32 v68, v74, v75
	v_cvt_pk_bf16_f32 v69, v76, v77
	v_cvt_pk_bf16_f32 v70, v70, v71
	v_cvt_pk_bf16_f32 v71, v72, v73
	v_cvt_pk_bf16_f32 v72, v84, v85
	v_cvt_pk_bf16_f32 v73, v86, v87
	s_waitcnt lgkmcnt(0)
	global_store_dwordx4 v[238:239], v[230:233], off
	global_store_dwordx4 v[238:239], v[234:237], off offset:256
	ds_bpermute_b32 v230, v214, v66
	ds_bpermute_b32 v231, v214, v67
	ds_bpermute_b32 v232, v214, v68
	ds_bpermute_b32 v233, v214, v69
	ds_bpermute_b32 v234, v214, v70
	ds_bpermute_b32 v235, v214, v71
	ds_bpermute_b32 v236, v214, v72
	ds_bpermute_b32 v237, v214, v73
	v_lshl_add_u64 v[238:239], v[250:251], 0, v[82:83]
; __device__ __forceinline__ float ss_rinv(u64 v) { return __builtin_amdgcn_rsqf((float)v * SS_INV + 1e-6f); }
; __device__ __forceinline__ unsigned cvtpk(float lo, float hi) { f32x2 v = {lo, hi}; bf16x2_t b = __builtin_convertvector(v, bf16x2_t); return __builtin_bit_cast(unsigned, b); }
;     __device__ __forceinline__ void operator()(const f32x4 (&acc)[2][2][4][2], const pg8::Unit& u, int wr, int wc, int fr, int fq) const {
;     ...
;                 const int lrow = u.pm * 256 + ai * 128 + wr * 64 + m * 16 + fr, grow = row_base + lrow;
;                 if (grow >= MREAL) continue;
;                 const float ri = ss_rinv(rowss[grow]);
; #pragma unroll
;                 for (int bj = 0; bj < 2; ++bj) {
;                     const int col0 = u.pn * 256 + bj * 128 + wc * 32 + 8 * fq;
;                     f32x4 v0 = acc[ai][bj][m][0] * ri, v1 = acc[ai][bj][m][1] * ri;
;                     if (MODE == 1) {
; #pragma unroll
;                         for (int i = 0; i < 4; ++i) { const float a = fmaxf(v0[i], 0.f), b = fmaxf(v1[i], 0.f); v0[i] = a * a; v1[i] = b * b; }
;                         u32x4 w; w.x = cvtpk(v0[0], v0[1]); w.y = cvtpk(v0[2], v0[3]); w.z = cvtpk(v1[0], v1[1]); w.w = cvtpk(v1[2], v1[3]);
;                         *(u32x4*)(O + (size_t)lrow * DFF + col0) = w;
.LBB0_2043:
	s_or_b64 exec, exec, s[36:37]
	v_add_u32_e32 v66, 0x80, v142
	v_add_u32_e32 v68, s66, v66
	v_cmp_gt_i32_e32 vcc, s54, v68
	s_and_saveexec_b64 s[36:37], vcc
	s_cbranch_execz .LBB0_2045
	v_mov_b64_e32 v[68:69], v[178:179]
	v_ffbh_u32_e32 v67, v69
	v_min_u32_e32 v70, 32, v67
	v_lshlrev_b64 v[68:69], v70, v[68:69]
	v_min_u32_e32 v67, 1, v68
	v_or_b32_e32 v67, v69, v67
	v_cvt_f32_u32_e32 v68, v67
	v_sub_u32_e32 v69, 32, v70
	v_ashrrev_i32_e32 v67, 31, v66
	v_lshlrev_b64 v[66:67], 13, v[66:67]
	v_ldexp_f32 v68, v68, v69
	v_fmamk_f32 v68, v68, 0x30800000, v203
	v_rsq_f32_e32 v68, v68
	v_lshl_add_u64 v[66:67], s[8:9], 0, v[66:67]
	v_lshl_add_u64 v[66:67], v[140:141], 1, v[66:67]
	v_pk_mul_f32 v[64:65], v[64:65], v[68:69] op_sel_hi:[1,0]
	v_pk_mul_f32 v[62:63], v[62:63], v[68:69] op_sel_hi:[1,0]
	v_pk_mul_f32 v[60:61], v[60:61], v[68:69] op_sel_hi:[1,0]
	v_pk_mul_f32 v[58:59], v[58:59], v[68:69] op_sel_hi:[1,0]
	v_pk_mul_f32 v[56:57], v[56:57], v[68:69] op_sel_hi:[1,0]
	v_pk_mul_f32 v[54:55], v[54:55], v[68:69] op_sel_hi:[1,0]
	v_pk_mul_f32 v[52:53], v[52:53], v[68:69] op_sel_hi:[1,0]
	v_pk_mul_f32 v[50:51], v[50:51], v[68:69] op_sel_hi:[1,0]
	v_max_f32_e32 v62, 0, v62
	v_max_f32_e32 v58, 0, v58
	v_max_f32_e32 v63, 0, v63
	v_max_f32_e32 v59, 0, v59
	v_max_f32_e32 v64, 0, v64
	v_max_f32_e32 v60, 0, v60
	v_max_f32_e32 v65, 0, v65
	v_max_f32_e32 v61, 0, v61
	v_max_f32_e32 v54, 0, v54
	v_max_f32_e32 v50, 0, v50
	v_max_f32_e32 v55, 0, v55
	v_max_f32_e32 v51, 0, v51
	v_max_f32_e32 v56, 0, v56
	v_max_f32_e32 v52, 0, v52
	v_max_f32_e32 v57, 0, v57
	v_max_f32_e32 v53, 0, v53
	v_pk_mul_f32 v[62:63], v[62:63], v[62:63]
	v_pk_mul_f32 v[58:59], v[58:59], v[58:59]
	v_pk_mul_f32 v[64:65], v[64:65], v[64:65]
	v_pk_mul_f32 v[60:61], v[60:61], v[60:61]
	v_pk_mul_f32 v[54:55], v[54:55], v[54:55]
	v_pk_mul_f32 v[68:69], v[50:51], v[50:51]
	v_pk_mul_f32 v[56:57], v[56:57], v[56:57]
	v_pk_mul_f32 v[70:71], v[52:53], v[52:53]
	v_cvt_pk_bf16_f32 v50, v62, v63
	v_cvt_pk_bf16_f32 v51, v64, v65
	v_cvt_pk_bf16_f32 v52, v58, v59
	v_cvt_pk_bf16_f32 v53, v60, v61
	v_cvt_pk_bf16_f32 v54, v54, v55
	v_cvt_pk_bf16_f32 v55, v56, v57
	v_cvt_pk_bf16_f32 v56, v68, v69
	v_cvt_pk_bf16_f32 v57, v70, v71
	s_waitcnt lgkmcnt(0)
	global_store_dwordx4 v[238:239], v[230:233], off
	global_store_dwordx4 v[238:239], v[234:237], off offset:256
	ds_bpermute_b32 v230, v214, v50
	ds_bpermute_b32 v231, v214, v51
	ds_bpermute_b32 v232, v214, v52
	ds_bpermute_b32 v233, v214, v53
	ds_bpermute_b32 v234, v214, v54
	ds_bpermute_b32 v235, v214, v55
	ds_bpermute_b32 v236, v214, v56
	ds_bpermute_b32 v237, v214, v57
	v_lshl_add_u64 v[238:239], v[250:251], 0, v[66:67]
.LBB0_2045:
	s_or_b64 exec, exec, s[36:37]
	v_add_u32_e32 v50, 0x90, v142
	v_add_u32_e32 v52, s66, v50
	v_cmp_gt_i32_e32 vcc, s54, v52
	s_and_saveexec_b64 s[36:37], vcc
	s_cbranch_execz .LBB0_2047
	v_mov_b64_e32 v[52:53], v[180:181]
	v_ffbh_u32_e32 v51, v53
	v_min_u32_e32 v54, 32, v51
	v_lshlrev_b64 v[52:53], v54, v[52:53]
	v_min_u32_e32 v51, 1, v52
	v_or_b32_e32 v51, v53, v51
	v_cvt_f32_u32_e32 v52, v51
	v_sub_u32_e32 v53, 32, v54
	v_ashrrev_i32_e32 v51, 31, v50
	v_lshlrev_b64 v[50:51], 13, v[50:51]
	v_ldexp_f32 v52, v52, v53
	v_fmamk_f32 v52, v52, 0x30800000, v203
	v_rsq_f32_e32 v52, v52
	v_lshl_add_u64 v[50:51], s[8:9], 0, v[50:51]
	v_lshl_add_u64 v[50:51], v[140:141], 1, v[50:51]
	v_pk_mul_f32 v[48:49], v[48:49], v[52:53] op_sel_hi:[1,0]
	v_pk_mul_f32 v[46:47], v[46:47], v[52:53] op_sel_hi:[1,0]
	v_pk_mul_f32 v[44:45], v[44:45], v[52:53] op_sel_hi:[1,0]
	v_pk_mul_f32 v[42:43], v[42:43], v[52:53] op_sel_hi:[1,0]
	v_pk_mul_f32 v[40:41], v[40:41], v[52:53] op_sel_hi:[1,0]
	v_pk_mul_f32 v[38:39], v[38:39], v[52:53] op_sel_hi:[1,0]
	v_pk_mul_f32 v[36:37], v[36:37], v[52:53] op_sel_hi:[1,0]
	v_pk_mul_f32 v[34:35], v[34:35], v[52:53] op_sel_hi:[1,0]
	v_max_f32_e32 v46, 0, v46
	v_max_f32_e32 v42, 0, v42
	v_max_f32_e32 v47, 0, v47
	v_max_f32_e32 v43, 0, v43
	v_max_f32_e32 v48, 0, v48
	v_max_f32_e32 v44, 0, v44
	v_max_f32_e32 v49, 0, v49
	v_max_f32_e32 v45, 0, v45
	v_max_f32_e32 v38, 0, v38
	v_max_f32_e32 v34, 0, v34
	v_max_f32_e32 v39, 0, v39
	v_max_f32_e32 v35, 0, v35
	v_max_f32_e32 v40, 0, v40
	v_max_f32_e32 v36, 0, v36
	v_max_f32_e32 v41, 0, v41
	v_max_f32_e32 v37, 0, v37
	v_pk_mul_f32 v[46:47], v[46:47], v[46:47]
	v_pk_mul_f32 v[42:43], v[42:43], v[42:43]
	v_pk_mul_f32 v[48:49], v[48:49], v[48:49]
	v_pk_mul_f32 v[44:45], v[44:45], v[44:45]
	v_pk_mul_f32 v[38:39], v[38:39], v[38:39]
	v_pk_mul_f32 v[52:53], v[34:35], v[34:35]
	v_pk_mul_f32 v[40:41], v[40:41], v[40:41]
	v_pk_mul_f32 v[54:55], v[36:37], v[36:37]
	v_cvt_pk_bf16_f32 v34, v46, v47
	v_cvt_pk_bf16_f32 v35, v48, v49
	v_cvt_pk_bf16_f32 v36, v42, v43
	v_cvt_pk_bf16_f32 v37, v44, v45
	v_cvt_pk_bf16_f32 v38, v38, v39
	v_cvt_pk_bf16_f32 v39, v40, v41
	v_cvt_pk_bf16_f32 v40, v52, v53
	v_cvt_pk_bf16_f32 v41, v54, v55
	s_waitcnt lgkmcnt(0)
	global_store_dwordx4 v[238:239], v[230:233], off
	global_store_dwordx4 v[238:239], v[234:237], off offset:256
	ds_bpermute_b32 v230, v214, v34
	ds_bpermute_b32 v231, v214, v35
	ds_bpermute_b32 v232, v214, v36
	ds_bpermute_b32 v233, v214, v37
	ds_bpermute_b32 v234, v214, v38
	ds_bpermute_b32 v235, v214, v39
	ds_bpermute_b32 v236, v214, v40
	ds_bpermute_b32 v237, v214, v41
	v_lshl_add_u64 v[238:239], v[250:251], 0, v[50:51]
; __device__ __forceinline__ float ss_rinv(u64 v) { return __builtin_amdgcn_rsqf((float)v * SS_INV + 1e-6f); }
; __device__ __forceinline__ unsigned cvtpk(float lo, float hi) { f32x2 v = {lo, hi}; bf16x2_t b = __builtin_convertvector(v, bf16x2_t); return __builtin_bit_cast(unsigned, b); }
; #define PG8_BAR __builtin_amdgcn_s_barrier()
; template <class Epi, bool ALIGN_EPI = true>
; __device__ __forceinline__ void gemm_phase(PG8_LAS unsigned char* lds, const Gemm g, const StaticOrder& S, const Epi& E) {
;     ...
;         cur = nxt; cA = nA; cB = nB; ++ui;
;         if constexpr (ALIGN_EPI) { if (wr == 1) PG8_BAR; }
;     __device__ __forceinline__ void operator()(const f32x4 (&acc)[2][2][4][2], const pg8::Unit& u, int wr, int wc, int fr, int fq) const {
;     ...
;                 const int lrow = u.pm * 256 + ai * 128 + wr * 64 + m * 16 + fr, grow = row_base + lrow;
;                 if (grow >= MREAL) continue;
;                 const float ri = ss_rinv(rowss[grow]);
; #pragma unroll
;                 for (int bj = 0; bj < 2; ++bj) {
;                     const int col0 = u.pn * 256 + bj * 128 + wc * 32 + 8 * fq;
;                     f32x4 v0 = acc[ai][bj][m][0] * ri, v1 = acc[ai][bj][m][1] * ri;
;                     if (MODE == 1) {
; #pragma unroll
;                         for (int i = 0; i < 4; ++i) { const float a = fmaxf(v0[i], 0.f), b = fmaxf(v1[i], 0.f); v0[i] = a * a; v1[i] = b * b; }
;                         u32x4 w; w.x = cvtpk(v0[0], v0[1]); w.y = cvtpk(v0[2], v0[3]); w.z = cvtpk(v1[0], v1[1]); w.w = cvtpk(v1[2], v1[3]);
;                         *(u32x4*)(O + (size_t)lrow * DFF + col0) = w;
.LBB0_2047:
	s_or_b64 exec, exec, s[36:37]
	v_add_u32_e32 v34, 0xa0, v142
	v_add_u32_e32 v36, s66, v34
	v_cmp_gt_i32_e32 vcc, s54, v36
	s_and_saveexec_b64 s[36:37], vcc
	s_cbranch_execz .LBB0_2049
	v_mov_b64_e32 v[36:37], v[182:183]
	v_ffbh_u32_e32 v35, v37
	v_min_u32_e32 v38, 32, v35
	v_lshlrev_b64 v[36:37], v38, v[36:37]
	v_min_u32_e32 v35, 1, v36
	v_or_b32_e32 v35, v37, v35
	v_cvt_f32_u32_e32 v36, v35
	v_sub_u32_e32 v37, 32, v38
	v_ashrrev_i32_e32 v35, 31, v34
	v_lshlrev_b64 v[34:35], 13, v[34:35]
	v_ldexp_f32 v36, v36, v37
	v_fmamk_f32 v36, v36, 0x30800000, v203
	v_rsq_f32_e32 v36, v36
	v_lshl_add_u64 v[34:35], s[8:9], 0, v[34:35]
	v_lshl_add_u64 v[34:35], v[140:141], 1, v[34:35]
	v_pk_mul_f32 v[30:31], v[30:31], v[36:37] op_sel_hi:[1,0]
	v_pk_mul_f32 v[28:29], v[28:29], v[36:37] op_sel_hi:[1,0]
	v_pk_mul_f32 v[26:27], v[26:27], v[36:37] op_sel_hi:[1,0]
	v_pk_mul_f32 v[24:25], v[24:25], v[36:37] op_sel_hi:[1,0]
	v_pk_mul_f32 v[22:23], v[22:23], v[36:37] op_sel_hi:[1,0]
	v_pk_mul_f32 v[20:21], v[20:21], v[36:37] op_sel_hi:[1,0]
	v_pk_mul_f32 v[18:19], v[18:19], v[36:37] op_sel_hi:[1,0]
	v_pk_mul_f32 v[16:17], v[16:17], v[36:37] op_sel_hi:[1,0]
	v_max_f32_e32 v28, 0, v28
	v_max_f32_e32 v24, 0, v24
	v_max_f32_e32 v29, 0, v29
	v_max_f32_e32 v25, 0, v25
	v_max_f32_e32 v30, 0, v30
	v_max_f32_e32 v26, 0, v26
	v_max_f32_e32 v31, 0, v31
	v_max_f32_e32 v27, 0, v27
	v_max_f32_e32 v20, 0, v20
	v_max_f32_e32 v16, 0, v16
	v_max_f32_e32 v21, 0, v21
	v_max_f32_e32 v17, 0, v17
	v_max_f32_e32 v22, 0, v22
	v_max_f32_e32 v18, 0, v18
	v_max_f32_e32 v23, 0, v23
	v_max_f32_e32 v19, 0, v19
	v_pk_mul_f32 v[28:29], v[28:29], v[28:29]
	v_pk_mul_f32 v[24:25], v[24:25], v[24:25]
	v_pk_mul_f32 v[30:31], v[30:31], v[30:31]
	v_pk_mul_f32 v[26:27], v[26:27], v[26:27]
	v_pk_mul_f32 v[20:21], v[20:21], v[20:21]
	v_pk_mul_f32 v[36:37], v[16:17], v[16:17]
	v_pk_mul_f32 v[22:23], v[22:23], v[22:23]
	v_pk_mul_f32 v[38:39], v[18:19], v[18:19]
	v_cvt_pk_bf16_f32 v16, v28, v29
	v_cvt_pk_bf16_f32 v17, v30, v31
	v_cvt_pk_bf16_f32 v18, v24, v25
	v_cvt_pk_bf16_f32 v19, v26, v27
	v_cvt_pk_bf16_f32 v20, v20, v21
	v_cvt_pk_bf16_f32 v21, v22, v23
	v_cvt_pk_bf16_f32 v22, v36, v37
	v_cvt_pk_bf16_f32 v23, v38, v39
	s_waitcnt lgkmcnt(0)
	global_store_dwordx4 v[238:239], v[230:233], off
	global_store_dwordx4 v[238:239], v[234:237], off offset:256
	ds_bpermute_b32 v230, v214, v16
	ds_bpermute_b32 v231, v214, v17
	ds_bpermute_b32 v232, v214, v18
	ds_bpermute_b32 v233, v214, v19
	ds_bpermute_b32 v234, v214, v20
	ds_bpermute_b32 v235, v214, v21
	ds_bpermute_b32 v236, v214, v22
	ds_bpermute_b32 v237, v214, v23
	v_lshl_add_u64 v[238:239], v[250:251], 0, v[34:35]
.LBB0_2049:
	s_or_b64 exec, exec, s[36:37]
	v_add_u32_e32 v16, 0xb0, v142
	v_add_u32_e32 v18, s66, v16
	v_cmp_gt_i32_e32 vcc, s54, v18
	s_and_saveexec_b64 s[36:37], vcc
	s_cbranch_execz .LBB0_2051
	v_mov_b64_e32 v[18:19], v[184:185]
	v_ffbh_u32_e32 v17, v19
	v_min_u32_e32 v20, 32, v17
	v_lshlrev_b64 v[18:19], v20, v[18:19]
	v_min_u32_e32 v17, 1, v18
	v_or_b32_e32 v17, v19, v17
	v_cvt_f32_u32_e32 v18, v17
	v_sub_u32_e32 v19, 32, v20
	v_ashrrev_i32_e32 v17, 31, v16
	v_lshlrev_b64 v[16:17], 13, v[16:17]
	v_ldexp_f32 v18, v18, v19
	v_fmamk_f32 v18, v18, 0x30800000, v203
	v_rsq_f32_e32 v18, v18
	v_lshl_add_u64 v[16:17], s[8:9], 0, v[16:17]
	v_lshl_add_u64 v[16:17], v[140:141], 1, v[16:17]
	v_pk_mul_f32 v[14:15], v[14:15], v[18:19] op_sel_hi:[1,0]
	v_pk_mul_f32 v[12:13], v[12:13], v[18:19] op_sel_hi:[1,0]
	v_pk_mul_f32 v[10:11], v[10:11], v[18:19] op_sel_hi:[1,0]
	v_pk_mul_f32 v[8:9], v[8:9], v[18:19] op_sel_hi:[1,0]
	v_pk_mul_f32 v[6:7], v[6:7], v[18:19] op_sel_hi:[1,0]
	v_pk_mul_f32 v[4:5], v[4:5], v[18:19] op_sel_hi:[1,0]
	v_pk_mul_f32 v[2:3], v[2:3], v[18:19] op_sel_hi:[1,0]
	v_pk_mul_f32 v[0:1], v[0:1], v[18:19] op_sel_hi:[1,0]
	v_max_f32_e32 v12, 0, v12
	v_max_f32_e32 v8, 0, v8
	v_max_f32_e32 v13, 0, v13
	v_max_f32_e32 v9, 0, v9
	v_max_f32_e32 v14, 0, v14
	v_max_f32_e32 v10, 0, v10
	v_max_f32_e32 v15, 0, v15
	v_max_f32_e32 v11, 0, v11
	v_max_f32_e32 v4, 0, v4
	v_max_f32_e32 v0, 0, v0
	v_max_f32_e32 v5, 0, v5
	v_max_f32_e32 v1, 0, v1
	v_max_f32_e32 v6, 0, v6
	v_max_f32_e32 v2, 0, v2
	v_max_f32_e32 v7, 0, v7
	v_max_f32_e32 v3, 0, v3
	v_pk_mul_f32 v[12:13], v[12:13], v[12:13]
	v_pk_mul_f32 v[8:9], v[8:9], v[8:9]
	v_pk_mul_f32 v[14:15], v[14:15], v[14:15]
	v_pk_mul_f32 v[10:11], v[10:11], v[10:11]
	v_pk_mul_f32 v[4:5], v[4:5], v[4:5]
	v_pk_mul_f32 v[18:19], v[0:1], v[0:1]
	v_pk_mul_f32 v[6:7], v[6:7], v[6:7]
	v_pk_mul_f32 v[20:21], v[2:3], v[2:3]
	v_cvt_pk_bf16_f32 v0, v12, v13
	v_cvt_pk_bf16_f32 v1, v14, v15
	v_cvt_pk_bf16_f32 v2, v8, v9
	v_cvt_pk_bf16_f32 v3, v10, v11
	v_cvt_pk_bf16_f32 v4, v4, v5
	v_cvt_pk_bf16_f32 v5, v6, v7
	v_cvt_pk_bf16_f32 v6, v18, v19
	v_cvt_pk_bf16_f32 v7, v20, v21
	s_waitcnt lgkmcnt(0)
	global_store_dwordx4 v[238:239], v[230:233], off
	global_store_dwordx4 v[238:239], v[234:237], off offset:256
	ds_bpermute_b32 v230, v214, v0
	ds_bpermute_b32 v231, v214, v1
	ds_bpermute_b32 v232, v214, v2
	ds_bpermute_b32 v233, v214, v3
	ds_bpermute_b32 v234, v214, v4
	ds_bpermute_b32 v235, v214, v5
	ds_bpermute_b32 v236, v214, v6
	ds_bpermute_b32 v237, v214, v7
	v_lshl_add_u64 v[238:239], v[250:251], 0, v[16:17]
.LBB0_2051:
	s_or_b64 exec, exec, s[36:37]
	s_cmp_eq_u32 s95, 0
	s_cbranch_scc1 .Lup_noflush
	s_waitcnt lgkmcnt(0)
	global_store_dwordx4 v[238:239], v[230:233], off
	global_store_dwordx4 v[238:239], v[234:237], off offset:256
.Lup_noflush:
	s_andn2_b64 vcc, exec, s[2:3]
	s_mov_b64 s[2:3], -1
	s_cbranch_vccnz .LBB0_2028
	s_andn2_b64 vcc, exec, s[6:7]
	s_cbranch_vccnz .LBB0_2027
	s_barrier
	s_branch .LBB0_2027
